# ssd_out unit-top counted wait: vmcnt(4) instead of vmcnt(0), the four output stores of the previous unit are no longer drained before the next unit starts
# speedup vs baseline: 1.0013x; 1.0013x over previous
.LBB0_438:
	s_add_i32 s0, s5, 0xffffff00
	s_lshr_b32 s0, s0, 6
	s_add_i32 s0, s0, 8
	s_lshr_b32 s1, s4, 8
	s_cmpk_lt_u32 s4, 0x800
	s_cselect_b32 s6, 31, 63
	s_cselect_b32 s0, s1, s0
	s_and_b32 s1, s6, s5
	s_lshl_b32 s4, s0, 4
	s_lshl_b32 s5, s86, 1
	s_or_b32 s4, s4, s5
	s_lshl_b32 s5, s4, 5
	s_lshl_b32 s4, s4, 6
	s_add_i32 s7, s4, 0xfffff000
	s_or_b32 s8, s5, 32
	s_addk_i32 s4, 0xf040
	s_cmp_lt_u32 s0, 8
	s_waitcnt vmcnt(0)
	v_mul_f32_e32 v0, 0x3fb8aa3b, v0
	s_cselect_b32 s0, s5, s7
	v_exp_f32_e32 v0, v0
	s_cselect_b32 s5, s8, s4
	s_or_b32 s4, s0, s1
	s_sub_i32 s0, s6, s1
	s_lshr_b32 s10, s86, 2
	s_add_i32 s6, s0, s5
	v_mul_f32_e32 v1, 0x3fb8aa3b, v1
	v_exp_f32_e32 v1, v1
	s_add_u32 s8, s66, 0x17c00000
	v_xor_b32_e32 v182, 0x80000000, v0
	v_add_u32_e32 v40, s33, v16
	v_and_b32_e32 v64, 15, v57
	v_lshlrev_b32_e32 v0, 3, v16
	s_addc_u32 s9, s67, 0
	s_lshl_b32 s0, s72, 4
	v_and_b32_e32 v56, 56, v0
	v_add_u32_e32 v0, 0x400, v40
	v_or_b32_e32 v169, s0, v64
	s_add_i32 s0, s90, s0
	s_lshl_b32 s68, s10, 8
	v_mov_b32_e32 v145, 0
	v_ashrrev_i32_e32 v167, 4, v0
	v_add_u32_e32 v0, 0x600, v40
	v_or_b32_e32 v144, s0, v64
	s_add_u32 s0, s66, 0x16400000
	v_xor_b32_e32 v178, 0x80000000, v1
	v_ashrrev_i32_e32 v168, 4, v0
	v_lshlrev_b64 v[0:1], 9, v[144:145]
	v_writelane_b32 v253, s8, 55
	s_addc_u32 s1, s67, 0
	v_lshlrev_b32_e32 v16, 4, v16
	v_writelane_b32 v253, s9, 56
	v_lshl_add_u64 v[0:1], s[8:9], 0, v[0:1]
	s_add_u32 s8, s0, s68
	s_addc_u32 s9, s1, 0
	s_ashr_i32 s7, s6, 31
	s_lshl_b64 s[6:7], s[6:7], 14
	s_add_u32 s6, s96, s6
	s_addc_u32 s7, s97, s7
	s_ashr_i32 s5, s4, 31
	s_lshl_b64 s[4:5], s[4:5], 14
	v_and_b32_e32 v144, 0xf0, v16
	s_add_u32 s4, s96, s4
	v_lshl_add_u64 v[28:29], s[8:9], 0, v[144:145]
	s_addc_u32 s5, s97, s5
	s_mul_i32 s10, s10, 0x1800000
	v_readlane_b32 s8, v253, 41
	v_readlane_b32 s9, v253, 42
	s_add_u32 s8, s8, s10
	v_add_u32_e32 v32, 0x200, v40
	s_addc_u32 s9, s9, 0
	s_lshl_b32 s10, s86, 7
	v_ashrrev_i32_e32 v164, 3, v32
	s_and_b32 s10, s10, 0x180
	v_ashrrev_i32_e32 v65, 4, v57
	s_add_u32 s8, s8, s10
	v_add_u32_e32 v42, s90, v164
	v_lshlrev_b32_e32 v146, 3, v65
	s_addc_u32 s9, s9, 0
	v_lshlrev_b32_e32 v62, 1, v56
	v_mov_b32_e32 v63, v145
	v_ashrrev_i32_e32 v43, 31, v42
	v_ashrrev_i32_e32 v41, 31, v40
	v_ashrrev_i32_e32 v33, 31, v32
	v_ashrrev_i32_e32 v147, 31, v146
	v_lshl_add_u64 v[0:1], v[0:1], 0, s[68:69]
	v_lshl_add_u64 v[52:53], s[8:9], 0, v[62:63]
	v_lshlrev_b64 v[42:43], 9, v[42:43]
	v_ashrrev_i32_e32 v163, 3, v40
	v_lshlrev_b64 v[58:59], 3, v[40:41]
	v_ashrrev_i32_e32 v165, 4, v40
	v_lshl_add_u64 v[12:13], v[146:147], 1, v[0:1]
	v_lshlrev_b64 v[36:37], 4, v[32:33]
	v_lshl_add_u64 v[42:43], v[52:53], 0, v[42:43]
	v_lshlrev_b64 v[40:41], 4, v[40:41]
	v_add_u32_e32 v67, -1, v174
	v_lshlrev_b64 v[60:61], 3, v[32:33]
	v_ashrrev_i32_e32 v166, 4, v32
	global_load_dwordx4 v[0:3], v[12:13], off offset:192
	global_load_dwordx4 v[4:7], v[12:13], off offset:128
	global_load_dwordx4 v[8:11], v[12:13], off offset:64
	s_nop 0
	global_load_dwordx4 v[12:15], v[12:13], off
	v_lshl_add_u64 v[32:33], s[6:7], 0, v[36:37]
	v_lshl_add_u64 v[36:37], s[4:5], 0, v[36:37]
	global_load_dwordx4 v[44:47], v[42:43], off
	v_lshl_add_u64 v[42:43], s[6:7], 0, v[40:41]
	v_lshl_add_u64 v[40:41], s[4:5], 0, v[40:41]
	v_and_b32_e32 v63, 63, v174
	v_cmp_lt_i32_e32 vcc, v67, v246
	v_cmp_gt_i32_e64 s[4:5], 1, v57
	v_and_b32_e32 v68, -16, v57
	v_cndmask_b32_e32 v67, v67, v174, vcc
	v_cmp_ne_u32_e32 vcc, 63, v63
	v_writelane_b32 v253, s4, 57
	v_lshlrev_b32_e32 v170, 2, v67
	v_addc_co_u32_e32 v67, vcc, 0, v174, vcc
	v_writelane_b32 v253, s5, 58
	v_cmp_gt_i32_e64 s[4:5], 63, v57
	v_lshlrev_b32_e32 v171, 2, v67
	v_add_u32_e32 v67, -2, v174
	v_writelane_b32 v253, s4, 59
	v_cmp_lt_i32_e32 vcc, v67, v246
	v_add_u32_e32 v62, 0, v62
	v_writelane_b32 v253, s5, 60
	v_cmp_gt_i32_e64 s[4:5], 2, v57
	v_cndmask_b32_e32 v67, v67, v174, vcc
	v_cmp_gt_u32_e32 vcc, 62, v63
	v_writelane_b32 v253, s4, 61
	v_lshlrev_b32_e32 v172, 2, v67
	v_cndmask_b32_e64 v67, 0, 2, vcc
	v_writelane_b32 v253, s5, 62
	v_cmp_gt_i32_e64 s[4:5], 62, v57
	v_add_lshl_u32 v173, v67, v174, 2
	v_add_u32_e32 v67, -4, v174
	v_writelane_b32 v253, s4, 63
	v_cmp_lt_i32_e32 vcc, v67, v246
	v_lshl_add_u64 v[148:149], s[0:1], 0, v[144:145]
	v_writelane_b32 v254, s5, 0
	v_cmp_gt_i32_e64 s[4:5], 4, v57
	v_cndmask_b32_e32 v67, v67, v174, vcc
	v_cmp_gt_u32_e32 vcc, 60, v63
	v_writelane_b32 v254, s4, 1
	v_lshlrev_b32_e32 v175, 2, v67
	v_cndmask_b32_e64 v67, 0, 4, vcc
	v_writelane_b32 v254, s5, 2
	v_cmp_gt_i32_e64 s[4:5], 60, v57
	v_add_lshl_u32 v176, v67, v174, 2
	v_add_u32_e32 v67, -8, v174
	v_writelane_b32 v254, s4, 3
	v_cmp_lt_i32_e32 vcc, v67, v246
	v_add_u32_e32 v186, 0, v68
	v_writelane_b32 v254, s5, 4
	v_cmp_gt_i32_e64 s[4:5], 8, v57
	v_cndmask_b32_e32 v67, v67, v174, vcc
	v_cmp_gt_u32_e32 vcc, 56, v63
	v_writelane_b32 v254, s4, 5
	v_lshlrev_b32_e32 v177, 2, v67
	v_cndmask_b32_e64 v67, 0, 8, vcc
	v_writelane_b32 v254, s5, 6
	v_cmp_gt_i32_e64 s[4:5], 56, v57
	v_add_lshl_u32 v179, v67, v174, 2
	v_add_u32_e32 v67, -16, v174
	v_writelane_b32 v254, s4, 7
	v_cmp_lt_i32_e32 vcc, v67, v246
	v_lshlrev_b32_e32 v150, 2, v65
	v_writelane_b32 v254, s5, 8
	v_cmp_gt_i32_e64 s[4:5], 16, v57
	v_cndmask_b32_e32 v67, v67, v174, vcc
	v_cmp_gt_u32_e32 vcc, 48, v63
	v_writelane_b32 v254, s4, 9
	v_mul_u32_u24_e32 v191, 0x110, v64
	v_cndmask_b32_e64 v63, 0, 16, vcc
	v_writelane_b32 v254, s5, 10
	v_cmp_gt_i32_e64 s[4:5], 48, v57
	v_add_lshl_u32 v181, v63, v174, 2
	v_subrev_u32_e32 v63, 32, v174
	v_writelane_b32 v254, s4, 11
	v_cmp_lt_i32_e32 vcc, v63, v246
	v_bfe_u32 v66, v57, 2, 2
	v_writelane_b32 v254, s5, 12
	v_cmp_gt_i32_e64 s[4:5], 32, v57
	v_cndmask_b32_e32 v63, v63, v174, vcc
	v_lshlrev_b32_e32 v183, 2, v63
	v_writelane_b32 v254, s4, 13
	v_mov_b32_e32 v63, 0x80
	v_lshl_or_b32 v184, v174, 2, v63
	v_writelane_b32 v254, s5, 14
	s_add_i32 s4, 0, 0x12800
	v_add_u32_e32 v63, s4, v144
	v_add_u32_e32 v69, s4, v68
	s_movk_i32 s4, 0x90
	v_mad_u64_u32 v[152:153], s[0:1], v163, s4, v[62:63]
	v_mad_u64_u32 v[154:155], s[0:1], v164, s4, v[62:63]
	s_mov_b32 s0, 0xa000
	s_nop 0
	v_add3_u32 v192, v186, v191, s0
	v_cmp_le_i32_e64 s[0:1], v150, v169
	s_add_i32 s5, 0, 0x16c00
	v_or_b32_e32 v65, v150, v66
	v_writelane_b32 v254, s0, 15
	v_or_b32_e32 v66, 16, v64
	v_mul_u32_u24_e32 v64, 0x88, v64
	v_writelane_b32 v254, s1, 16
	v_cmp_lt_i32_e64 s[0:1], v150, v169
	v_add_u32_e32 v68, s5, v68
	v_lshlrev_b32_e32 v64, 1, v64
	v_writelane_b32 v254, s0, 17
	v_add_u32_e32 v193, v69, v64
	v_add_u32_e32 v194, v68, v64
	v_writelane_b32 v254, s1, 18
	v_cmp_ge_i32_e64 s[0:1], v150, v169
	v_or_b32_e32 v64, 1, v150
	v_add_u32_e32 v16, s90, v168
	v_writelane_b32 v254, s0, 19
	v_add_u32_e32 v20, s90, v167
	v_ashrrev_i32_e32 v17, 31, v16
	v_writelane_b32 v254, s1, 20
	v_cmp_ge_i32_e64 s[0:1], v64, v169
	v_or_b32_e32 v64, 2, v150
	v_ashrrev_i32_e32 v21, 31, v20
	v_writelane_b32 v254, s0, 21
	v_lshlrev_b64 v[16:17], 9, v[16:17]
	v_lshlrev_b64 v[20:21], 9, v[20:21]
	v_writelane_b32 v254, s1, 22
	v_cmp_le_i32_e64 s[0:1], v64, v169
	v_lshl_add_u64 v[16:17], v[28:29], 0, v[16:17]
	v_lshl_add_u64 v[20:21], v[28:29], 0, v[20:21]
	v_writelane_b32 v254, s0, 23
	global_load_dwordx4 v[16:19], v[16:17], off
	v_add_u32_e32 v30, s90, v165
	v_writelane_b32 v254, s1, 24
	v_cmp_ge_i32_e64 s[0:1], v64, v169
	v_or_b32_e32 v64, 3, v150
	global_load_dwordx4 v[24:27], v[20:21], off
	v_writelane_b32 v254, s0, 25
	v_add_u32_e32 v20, s90, v166
	v_add_u32_e32 v54, s90, v163
	v_writelane_b32 v254, s1, 26
	v_cmp_le_i32_e64 s[0:1], v64, v169
	v_ashrrev_i32_e32 v21, 31, v20
	v_ashrrev_i32_e32 v31, 31, v30
	v_writelane_b32 v254, s0, 27
	v_ashrrev_i32_e32 v55, 31, v54
	v_lshlrev_b64 v[20:21], 9, v[20:21]
	v_writelane_b32 v254, s1, 28
	v_cmp_ge_i32_e64 s[0:1], v64, v169
	v_add_u32_e32 v64, 16, v150
	v_lshlrev_b64 v[30:31], 9, v[30:31]
	v_writelane_b32 v254, s0, 29
	v_lshlrev_b64 v[54:55], 9, v[54:55]
	v_lshl_add_u64 v[20:21], v[28:29], 0, v[20:21]
	v_writelane_b32 v254, s1, 30
	v_cmp_le_i32_e64 s[0:1], v64, v169
	v_lshl_add_u64 v[28:29], v[28:29], 0, v[30:31]
	v_lshl_add_u64 v[52:53], v[52:53], 0, v[54:55]
	v_writelane_b32 v254, s0, 31
	s_cmpk_lt_u32 s76, 0x80
	global_load_dwordx4 v[20:23], v[20:21], off
	v_writelane_b32 v254, s1, 32
	v_cmp_ge_i32_e64 s[0:1], v64, v169
	v_add_u32_e32 v64, 17, v150
	global_load_dwordx4 v[28:31], v[28:29], off
	v_writelane_b32 v254, s0, 33
	global_load_dwordx4 v[32:35], v[32:33], off
	v_lshlrev_b32_e32 v57, 3, v57
	v_writelane_b32 v254, s1, 34
	v_cmp_le_i32_e64 s[0:1], v64, v169
	global_load_dwordx4 v[36:39], v[36:37], off
	v_and_b32_e32 v57, 24, v57
	v_writelane_b32 v254, s0, 35
	global_load_dwordx4 v[48:51], v[42:43], off
	v_lshlrev_b32_e32 v180, 2, v67
	v_writelane_b32 v254, s1, 36
	v_cmp_ge_i32_e64 s[0:1], v64, v169
	v_add_u32_e32 v64, 18, v150
	global_load_dwordx4 v[40:43], v[40:41], off
	v_writelane_b32 v254, s0, 37
	global_load_dwordx4 v[52:55], v[52:53], off
	v_add_u32_e32 v67, s5, v144
	v_writelane_b32 v254, s1, 38
	v_cmp_le_i32_e64 s[0:1], v64, v169
	s_movk_i32 s5, 0x110
	v_mul_lo_u32 v153, v165, s5
	v_writelane_b32 v254, s0, 39
	v_mul_lo_u32 v155, v166, s5
	v_add_u32_e32 v185, 0, v144
	v_writelane_b32 v254, s1, 40
	v_cmp_ge_i32_e64 s[0:1], v64, v169
	v_add_u32_e32 v64, 19, v150
	v_add_u32_e32 v187, v63, v153
	v_writelane_b32 v254, s0, 41
	v_add_u32_e32 v189, v63, v155
	v_mul_lo_u32 v62, v167, s5
	v_writelane_b32 v254, s1, 42
	v_cmp_le_i32_e64 s[0:1], v64, v169
	v_mul_lo_u32 v63, v168, s5
	v_ashrrev_i32_e32 v151, 31, v150
	v_writelane_b32 v254, s0, 43
	v_add_u32_e32 v188, v67, v153
	v_add_u32_e32 v190, v67, v155
	v_writelane_b32 v254, s1, 44
	v_cmp_ge_i32_e64 s[0:1], v64, v169
	v_mul_lo_u32 v64, v65, s4
	v_add3_u32 v195, 0, v57, v64
	v_writelane_b32 v254, s0, 45
	v_add_u32_e32 v57, 32, v150
	v_add_u32_e32 v202, v185, v62
	v_writelane_b32 v254, s1, 46
	s_cselect_b64 s[0:1], -1, 0
	v_writelane_b32 v254, s0, 47
	s_cmpk_gt_u32 s76, 0x7f
	v_add_u32_e32 v203, v185, v63
	v_writelane_b32 v254, s1, 48
	s_cselect_b64 s[0:1], -1, 0
	v_writelane_b32 v254, s0, 49
	s_cmpk_lt_u32 s76, 0x100
	v_lshlrev_b32_e32 v144, 1, v56
	v_writelane_b32 v254, s1, 50
	v_cmp_le_i32_e64 s[0:1], v57, v169
	v_lshlrev_b64 v[156:157], 1, v[58:59]
	v_lshlrev_b64 v[158:159], 1, v[60:61]
	v_writelane_b32 v254, s0, 51
	s_mov_b32 s70, 0
	s_nop 0
	v_writelane_b32 v254, s1, 52
	v_cmp_ge_i32_e64 s[0:1], v57, v169
	v_add_u32_e32 v57, 33, v150
	s_nop 0
	v_writelane_b32 v254, s0, 53
	s_nop 1
	v_writelane_b32 v254, s1, 54
	v_cmp_le_i32_e64 s[0:1], v57, v169
	s_nop 1
	v_writelane_b32 v254, s0, 55
	s_nop 1
	v_writelane_b32 v254, s1, 56
	v_cmp_ge_i32_e64 s[0:1], v57, v169
	v_add_u32_e32 v57, 34, v150
	s_nop 0
	v_writelane_b32 v254, s0, 57
	s_nop 1
	v_writelane_b32 v254, s1, 58
	v_cmp_le_i32_e64 s[0:1], v57, v169
	s_nop 1
	v_writelane_b32 v254, s0, 59
	s_nop 1
	v_writelane_b32 v254, s1, 60
	v_cmp_ge_i32_e64 s[0:1], v57, v169
	v_add_u32_e32 v57, 35, v150
	s_nop 0
	v_writelane_b32 v254, s0, 61
	s_nop 1
	v_writelane_b32 v254, s1, 62
	v_cmp_le_i32_e64 s[0:1], v57, v169
	s_nop 1
	v_writelane_b32 v254, s0, 63
	s_nop 1
	v_writelane_b32 v255, s1, 0
	v_cmp_ge_i32_e64 s[0:1], v57, v169
	v_add_u32_e32 v57, 48, v150
	s_nop 0
	v_writelane_b32 v255, s0, 1
	s_nop 1
	v_writelane_b32 v255, s1, 2
	v_cmp_le_i32_e64 s[0:1], v57, v169
	s_nop 1
	v_writelane_b32 v255, s0, 3
	s_nop 1
	v_writelane_b32 v255, s1, 4
	v_cmp_ge_i32_e64 s[0:1], v57, v169
	v_add_u32_e32 v57, 49, v150
	s_nop 0
	v_writelane_b32 v255, s0, 5
	s_nop 1
	v_writelane_b32 v255, s1, 6
	v_cmp_le_i32_e64 s[0:1], v57, v169
	s_nop 1
	v_writelane_b32 v255, s0, 7
	s_nop 1
	v_writelane_b32 v255, s1, 8
	v_cmp_ge_i32_e64 s[0:1], v57, v169
	v_add_u32_e32 v57, 50, v150
	s_nop 0
	v_writelane_b32 v255, s0, 9
	s_nop 1
	v_writelane_b32 v255, s1, 10
	v_cmp_le_i32_e64 s[0:1], v57, v169
	s_nop 1
	v_writelane_b32 v255, s0, 11
	s_nop 1
	v_writelane_b32 v255, s1, 12
	v_cmp_ge_i32_e64 s[0:1], v57, v169
	v_add_u32_e32 v57, 51, v150
	s_nop 0
	v_writelane_b32 v255, s0, 13
	s_nop 1
	v_writelane_b32 v255, s1, 14
	v_cmp_le_i32_e64 s[0:1], v57, v169
	s_nop 1
	v_writelane_b32 v255, s0, 15
	s_nop 1
	v_writelane_b32 v255, s1, 16
	v_cmp_ge_i32_e64 s[0:1], v57, v169
	v_add_u32_e32 v57, 64, v150
	s_nop 0
	v_writelane_b32 v255, s0, 17
	s_nop 1
	v_writelane_b32 v255, s1, 18
	s_cselect_b64 s[0:1], -1, 0
	v_writelane_b32 v255, s0, 19
	s_cmpk_gt_u32 s76, 0xff
	s_cselect_b64 s[72:73], -1, 0
	v_writelane_b32 v255, s1, 20
	v_cmp_le_i32_e64 s[0:1], v57, v169
	s_cmpk_lt_u32 s76, 0x180
	s_cselect_b64 s[74:75], -1, 0
	v_writelane_b32 v255, s0, 21
	s_cmpk_gt_u32 s76, 0x17f
	s_nop 0
	v_writelane_b32 v255, s1, 22
	v_cmp_ge_i32_e64 s[0:1], v57, v169
	v_add_u32_e32 v57, 0x41, v150
	s_nop 0
	v_writelane_b32 v255, s0, 23
	s_nop 1
	v_writelane_b32 v255, s1, 24
	v_cmp_le_i32_e64 s[0:1], v57, v169
	s_nop 1
	v_writelane_b32 v255, s0, 25
	s_nop 1
	v_writelane_b32 v255, s1, 26
	v_cmp_ge_i32_e64 s[0:1], v57, v169
	v_add_u32_e32 v57, 0x42, v150
	s_nop 0
	v_writelane_b32 v255, s0, 27
	s_nop 1
	v_writelane_b32 v255, s1, 28
	v_cmp_le_i32_e64 s[0:1], v57, v169
	s_nop 1
	v_writelane_b32 v255, s0, 29
	s_nop 1
	v_writelane_b32 v255, s1, 30
	v_cmp_ge_i32_e64 s[0:1], v57, v169
	v_add_u32_e32 v57, 0x43, v150
	s_nop 0
	v_writelane_b32 v255, s0, 31
	s_nop 1
	v_writelane_b32 v255, s1, 32
	v_cmp_le_i32_e64 s[0:1], v57, v169
	s_nop 1
	v_writelane_b32 v255, s0, 33
	s_nop 1
	v_writelane_b32 v255, s1, 34
	v_cmp_ge_i32_e64 s[0:1], v57, v169
	v_add_u32_e32 v57, 0x50, v150
	s_nop 0
	v_writelane_b32 v255, s0, 35
	s_nop 1
	v_writelane_b32 v255, s1, 36
	v_cmp_le_i32_e64 s[0:1], v57, v169
	s_nop 1
	v_writelane_b32 v255, s0, 37
	s_nop 1
	v_writelane_b32 v255, s1, 38
	v_cmp_ge_i32_e64 s[0:1], v57, v169
	v_add_u32_e32 v57, 0x51, v150
	s_nop 0
	v_writelane_b32 v255, s0, 39
	s_nop 1
	v_writelane_b32 v255, s1, 40
	v_cmp_le_i32_e64 s[0:1], v57, v169
	s_nop 1
	v_writelane_b32 v255, s0, 41
	s_nop 1
	v_writelane_b32 v255, s1, 42
	v_cmp_ge_i32_e64 s[0:1], v57, v169
	v_add_u32_e32 v57, 0x52, v150
	s_nop 0
	v_writelane_b32 v255, s0, 43
	s_nop 1
	v_writelane_b32 v255, s1, 44
	v_cmp_le_i32_e64 s[0:1], v57, v169
	s_nop 1
	v_writelane_b32 v255, s0, 45
	s_nop 1
	v_writelane_b32 v255, s1, 46
	v_cmp_ge_i32_e64 s[0:1], v57, v169
	v_add_u32_e32 v57, 0x53, v150
	s_nop 0
	v_writelane_b32 v255, s0, 47
	s_nop 1
	v_writelane_b32 v255, s1, 48
	v_cmp_le_i32_e64 s[0:1], v57, v169
	s_nop 1
	v_writelane_b32 v255, s0, 49
	s_nop 1
	v_writelane_b32 v255, s1, 50
	v_cmp_ge_i32_e64 s[0:1], v57, v169
	v_add_u32_e32 v57, 0x60, v150
	v_cmp_le_i32_e64 s[24:25], v57, v169
	v_cmp_ge_i32_e64 s[26:27], v57, v169
	v_add_u32_e32 v57, 0x61, v150
	v_cmp_le_i32_e64 s[28:29], v57, v169
	v_cmp_ge_i32_e64 s[30:31], v57, v169
	v_add_u32_e32 v57, 0x62, v150
	v_cmp_le_i32_e64 s[34:35], v57, v169
	v_cmp_ge_i32_e64 s[36:37], v57, v169
	v_add_u32_e32 v57, 0x63, v150
	v_cmp_le_i32_e64 s[38:39], v57, v169
	v_cmp_ge_i32_e64 s[40:41], v57, v169
	v_add_u32_e32 v57, 0x70, v150
	v_cmp_le_i32_e64 s[42:43], v57, v169
	v_cmp_ge_i32_e64 s[44:45], v57, v169
	v_add_u32_e32 v57, 0x71, v150
	v_cmp_le_i32_e64 s[46:47], v57, v169
	v_cmp_ge_i32_e64 s[48:49], v57, v169
	v_add_u32_e32 v57, 0x72, v150
	v_writelane_b32 v255, s0, 51
	v_cmp_le_i32_e64 s[50:51], v57, v169
	v_cmp_ge_i32_e64 s[52:53], v57, v169
	v_add_u32_e32 v57, 0x73, v150
	v_writelane_b32 v255, s1, 52
	v_cmp_le_i32_e64 s[54:55], v57, v169
	v_cmp_ge_i32_e64 s[56:57], v57, v169
	s_mov_b32 s0, s76
	v_mul_u32_u24_e32 v57, 0x88, v66
	s_cselect_b64 s[76:77], -1, 0
	s_cmpk_lt_u32 s0, 0x200
	v_lshlrev_b32_e32 v57, 1, v57
	s_cselect_b64 s[78:79], -1, 0
	v_add_u32_e32 v196, v69, v57
	v_add_u32_e32 v197, v68, v57
	v_add_u32_e32 v64, 0x1100, v57
	v_add_u32_e32 v57, 0x2200, v57
	s_add_u32 s88, s66, 0xd400000
	v_writelane_b32 v255, s0, 53
	v_add_u32_e32 v198, v69, v64
	v_add_u32_e32 v199, v68, v64
	v_add_u32_e32 v200, v69, v57
	v_add_u32_e32 v201, v68, v57
	s_addc_u32 s89, s67, 0
	s_waitcnt vmcnt(0)
	s_branch .LBB0_440

.LBB0_442:
	s_waitcnt lgkmcnt(0)
	s_barrier
	v_lshl_add_u32 v118, v163, 2, s91
	ds_read_b32 v108, v118 offset:1024
	s_waitcnt vmcnt(4)
	v_lshlrev_b32_e32 v110, 16, v52
	v_and_b32_e32 v111, 0xffff0000, v52
	v_lshlrev_b32_e32 v112, 16, v53
	v_and_b32_e32 v113, 0xffff0000, v53
	s_waitcnt lgkmcnt(0)
	v_pk_mul_f32 v[104:105], v[108:109], v[110:111] op_sel_hi:[0,1]
	v_pk_mul_f32 v[106:107], v[108:109], v[112:113] op_sel_hi:[0,1]
	v_lshlrev_b32_e32 v114, 16, v54
	v_and_b32_e32 v115, 0xffff0000, v54
	v_lshlrev_b32_e32 v116, 16, v55
	v_and_b32_e32 v117, 0xffff0000, v55
	v_cvt_pk_bf16_f32 v104, v104, v105
	v_cvt_pk_bf16_f32 v105, v106, v107
	v_pk_mul_f32 v[106:107], v[108:109], v[114:115] op_sel_hi:[0,1]
	v_pk_mul_f32 v[108:109], v[108:109], v[116:117] op_sel_hi:[0,1]
	v_cvt_pk_bf16_f32 v106, v106, v107
	v_cvt_pk_bf16_f32 v107, v108, v109
	ds_write_b128 v152, v[104:107] offset:4096
	ds_read_b32 v108, v118 offset:1536
	v_lshl_add_u32 v118, v164, 2, s91
	s_add_i32 s68, s85, -1
	s_and_b32 s68, s68, 3
	s_cmp_eq_u32 s68, 0
	s_waitcnt lgkmcnt(0)
	v_pk_mul_f32 v[104:105], v[108:109], v[110:111] op_sel_hi:[0,1]
	v_pk_mul_f32 v[106:107], v[108:109], v[112:113] op_sel_hi:[0,1]
	v_cvt_pk_bf16_f32 v104, v104, v105
	v_cvt_pk_bf16_f32 v105, v106, v107
	v_pk_mul_f32 v[106:107], v[108:109], v[114:115] op_sel_hi:[0,1]
	v_pk_mul_f32 v[108:109], v[108:109], v[116:117] op_sel_hi:[0,1]
	v_cvt_pk_bf16_f32 v106, v106, v107
	v_cvt_pk_bf16_f32 v107, v108, v109
	ds_write_b128 v152, v[104:107] offset:22528
	ds_write_b128 v187, v[40:43]
	ds_write_b128 v188, v[48:51]
	ds_read_b32 v108, v118 offset:1024
	v_lshlrev_b32_e32 v110, 16, v44
	v_and_b32_e32 v111, 0xffff0000, v44
	v_lshlrev_b32_e32 v112, 16, v45
	v_and_b32_e32 v113, 0xffff0000, v45
	s_waitcnt lgkmcnt(0)
	v_pk_mul_f32 v[104:105], v[108:109], v[110:111] op_sel_hi:[0,1]
	v_pk_mul_f32 v[106:107], v[108:109], v[112:113] op_sel_hi:[0,1]
	v_lshlrev_b32_e32 v114, 16, v46
	v_and_b32_e32 v115, 0xffff0000, v46
	v_lshlrev_b32_e32 v116, 16, v47
	v_and_b32_e32 v117, 0xffff0000, v47
	v_cvt_pk_bf16_f32 v104, v104, v105
	v_cvt_pk_bf16_f32 v105, v106, v107
	v_pk_mul_f32 v[106:107], v[108:109], v[114:115] op_sel_hi:[0,1]
	v_pk_mul_f32 v[108:109], v[108:109], v[116:117] op_sel_hi:[0,1]
	v_cvt_pk_bf16_f32 v106, v106, v107
	v_cvt_pk_bf16_f32 v107, v108, v109
	ds_write_b128 v154, v[104:107] offset:4096
	ds_read_b32 v108, v118 offset:1536
	s_cselect_b64 s[82:83], -1, 0
	s_cmp_lg_u32 s68, 0
	s_waitcnt lgkmcnt(0)
	v_pk_mul_f32 v[104:105], v[108:109], v[110:111] op_sel_hi:[0,1]
	v_pk_mul_f32 v[106:107], v[108:109], v[112:113] op_sel_hi:[0,1]
	v_cvt_pk_bf16_f32 v104, v104, v105
	v_cvt_pk_bf16_f32 v105, v106, v107
	v_pk_mul_f32 v[106:107], v[108:109], v[114:115] op_sel_hi:[0,1]
	v_pk_mul_f32 v[108:109], v[108:109], v[116:117] op_sel_hi:[0,1]
	v_cvt_pk_bf16_f32 v106, v106, v107
	v_cvt_pk_bf16_f32 v107, v108, v109
	ds_write_b128 v154, v[104:107] offset:22528
	ds_write_b128 v189, v[36:39]
	ds_write_b128 v190, v[32:35]
	s_cbranch_scc1 .LBB0_444
	v_add_u32_e32 v56, v185, v153
	ds_write_b128 v56, v[28:31] offset:40960
	v_add_u32_e32 v56, v185, v155
	ds_write_b128 v56, v[20:23] offset:40960
	ds_write_b128 v202, v[24:27] offset:40960
	ds_write_b128 v203, v[16:19] offset:40960
	v_mov_b64_e32 v[58:59], v[2:3]
	v_mov_b64_e32 v[62:63], v[6:7]
	v_mov_b64_e32 v[66:67], v[10:11]
	v_mov_b64_e32 v[70:71], v[14:15]
	v_mov_b64_e32 v[56:57], v[0:1]
	v_mov_b64_e32 v[60:61], v[4:5]
	v_mov_b64_e32 v[64:65], v[8:9]
	v_mov_b64_e32 v[68:69], v[12:13]
